# MLA attention loop hand-scheduled: waves 0-3 matrix phase then softmax, waves 4-7 softmax then matrix phase; both halves prio 1
# speedup vs baseline: 1.0055x; 1.0003x over previous
; __device__ __forceinline__ float xhalf_max(float m) { auto rr = __builtin_amdgcn_permlane32_swap(__float_as_uint(m), __float_as_uint(m), false, false); return fmaxf(__uint_as_float(rr[0]), __uint_as_float(rr[1])); }
; __device__ __forceinline__ float max3f(float a, float b, float c) { float r; asm("v_max3_f32 %0, %1, %2, %3" : "=v"(r) : "v"(a), "v"(b), "v"(c)); return r; }
; __device__ __forceinline__ float max2f(float a, float b) { float r; asm("v_max_f32_e32 %0, %1, %2" : "=v"(r) : "v"(a), "v"(b)); return r; }
; template <int GRP, bool has_next> __device__ __forceinline__ void att_step(const AttCtx<GRP>& C, AttState<GRP>& S, int s, f32x16& P0, f32x16& P1, f32x16& PN0, f32x16& PN1, u32x4& kreg, u32x4& preg, u32x4& vreg) {
;     ...
;     if ((t & 7) == 0) {
;         float ma = max3f(P0[0], P0[1], P0[2]), mb = max3f(P0[3], P0[4], P0[5]), mc = max3f(P1[0], P1[1], P1[2]), md = max3f(P1[3], P1[4], P1[5]);
;         ma = max3f(ma, P0[6], P0[7]); mb = max3f(mb, P0[8], P0[9]); mc = max3f(mc, P1[6], P1[7]); md = max3f(md, P1[8], P1[9]);
;         ma = max3f(ma, P0[10], P0[11]); mb = max3f(mb, P0[12], P0[13]); mc = max3f(mc, P1[10], P1[11]); md = max3f(md, P1[12], P1[13]);
;         ma = max3f(ma, P0[14], P0[15]); mc = max3f(mc, P1[14], P1[15]); ma = max3f(ma, mb, mc); mb = md;
;         const float mx = xhalf_max(max2f(ma, mb));
;         const int up = __any(mx > THR), dn = (t == 0) ? __any(mx < -THR) : 0;
; template <int GRP> ...
;     ...
;     if (wid >= 4) __builtin_amdgcn_s_setprio(1);
;     asm volatile("s_nop 15\n\ts_nop 7" : "+v"(pa0), "+v"(pa1));
;     for (int s = 0; s < NSTEP - 2; s += 2) { att_step<GRP, true>(C, S, s, pa0, pa1, pb0, pb1, kA, pA, vA); att_step<GRP, true>(C, S, s + 1, pb0, pb1, pa0, pa1, kA, pA, vA); }
.LBB0_775:
	v_lshlrev_b32_e32 v4, 3, v2
	s_and_b32 s0, s58, 7
	v_mad_u32_u24 v3, v3, s37, v96
	v_mad_u64_u32 v[6:7], s[14:15], v16, s37, v[18:19]
	v_lshlrev_b32_e32 v96, 1, v4
	s_lshl_b32 s62, s0, 22
	s_lshl_b32 s60, s66, 2
	v_lshl_add_u64 v[164:165], v[0:1], 0, v[96:97]
	v_lshlrev_b64 v[0:1], 7, v[16:17]
	s_lshl_b64 s[14:15], s[10:11], 1
	v_lshlrev_b64 v[8:9], 11, v[152:153]
	v_lshl_add_u64 v[0:1], s[62:63], 0, v[0:1]
	s_add_u32 s14, s8, s14
	v_mov_b32_e32 v5, v97
	v_lshl_add_u64 v[154:155], s[48:49], 0, v[8:9]
	v_lshl_or_b32 v0, v19, 4, v0
	s_addc_u32 s15, s9, s15
	v_mov_b32_e32 v175, 0
	s_mov_b32 s72, 0
	v_cmp_eq_u32_e64 s[0:1], 0, v2
	v_lshlrev_b32_e32 v156, 2, v2
	v_lshl_add_u64 v[162:163], v[154:155], 0, v[4:5]
	v_lshl_add_u64 v[166:167], s[14:15], 0, v[0:1]
	s_add_i32 s70, s10, 0x4000
	s_movk_i32 s67, 0x2000
	v_add_u32_e32 v157, 0, v3
	v_add_u32_e32 v169, 0, v6
	v_mov_b32_e32 v168, 0
	s_mov_b32 s69, 0
	v_mov_b32_e32 v170, 0
	v_mov_b32_e32 v0, 0
	v_mov_b32_e32 v1, v175
	v_mov_b32_e32 v2, v175
	v_mov_b32_e32 v3, v175
	v_mov_b32_e32 v4, v175
	v_mov_b32_e32 v5, v175
	v_mov_b32_e32 v6, v175
	v_mov_b32_e32 v7, v175
	v_mov_b32_e32 v8, v175
	v_mov_b32_e32 v9, v175
	v_mov_b32_e32 v10, v175
	v_mov_b32_e32 v11, v175
	v_mov_b32_e32 v12, v175
	v_mov_b32_e32 v13, v175
	v_mov_b32_e32 v14, v175
	v_mov_b32_e32 v15, v175
	v_mov_b32_e32 v16, 0
	v_mov_b32_e32 v17, v175
	v_mov_b32_e32 v18, v175
	v_mov_b32_e32 v19, v175
	v_mov_b32_e32 v20, v175
	v_mov_b32_e32 v21, v175
	v_mov_b32_e32 v22, v175
	v_mov_b32_e32 v23, v175
	v_mov_b32_e32 v24, v175
	v_mov_b32_e32 v25, v175
	v_mov_b32_e32 v26, v175
	v_mov_b32_e32 v27, v175
	v_mov_b32_e32 v28, v175
	v_mov_b32_e32 v29, v175
	v_mov_b32_e32 v30, v175
	v_mov_b32_e32 v31, v175
	s_nop 15
	s_nop 7
	s_waitcnt lgkmcnt(0)
	s_barrier
	v_readfirstlane_b32 s93, v254
	s_cmpk_gt_u32 s93, 0xff
	s_cbranch_scc1 .Lmla_T_entry
	s_setprio 1
	s_and_b32 s10, s69, 6
	s_cmp_lg_u32 s10, 0
	s_cbranch_scc1 .Lmla_nomax1
	v_max3_f32 v96, v48, v49, v50
	v_max3_f32 v99, v32, v33, v34
	v_max3_f32 v98, v51, v52, v53
	v_max3_f32 v252, v35, v36, v37
	s_and_b32 s14, s69, 56
	v_max3_f32 v96, v96, v54, v55
	v_max3_f32 v99, v99, v38, v39
	v_max3_f32 v98, v98, v56, v57
	v_max3_f32 v252, v252, v40, v41
	s_cmp_eq_u32 s14, 0
	v_max3_f32 v96, v96, v58, v59
	v_max3_f32 v99, v99, v42, v43
	v_max3_f32 v98, v98, v60, v61
	v_max3_f32 v252, v252, v44, v45
	s_cselect_b64 s[10:11], -1, 0
	v_max3_f32 v96, v96, v62, v63
	v_max3_f32 v99, v99, v46, v47
	s_cmp_lg_u32 s14, 0
	v_max3_f32 v96, v96, v98, v99
	s_nop 0
	v_max_f32_e32 v96, v96, v252
	s_nop 0
	v_mov_b32_e32 v98, v96
	s_nop 1
	v_permlane32_swap_b32_e32 v96, v98
	v_max_f32_e32 v98, v98, v98
	v_max_f32_e32 v96, v96, v96
	v_max_f32_e32 v96, v96, v98
	v_cmp_lt_f32_e32 vcc, s54, v96
	v_mov_b32_e32 v98, 0
	s_cbranch_scc1 .Lmla_mx2
	v_cmp_gt_f32_e64 s[14:15], s55, v96
	s_cmp_lg_u64 s[14:15], 0
	s_cselect_b64 s[14:15], -1, 0
	v_cndmask_b32_e64 v98, 0, 1, s[14:15]

; template <int GRP> ...
;     ...
;     if (wid >= 4) __builtin_amdgcn_s_setprio(1);
.Lmla_T_entry:
	s_setprio 1
